# FoX attention tile body rescheduled by hand: two score MFMA chains, packed f32 bias/max/exp-arg/rescale in place, no per-tile accumulator copies (bit-identical)
# speedup vs baseline: 1.0064x; 1.0064x over previous
.LBB0_318:
	s_or_b64 exec, exec, s[6:7]
	s_nop 0
	s_xor_b64 s[6:7], exec, -1
.LBB0_319:
	s_or_b64 exec, exec, s[2:3]
	s_andn2_b64 s[2:3], s[44:45], exec
	s_and_b64 s[6:7], s[6:7], exec
	s_nop 1
	s_or_b64 s[44:45], s[2:3], s[6:7]

.LBB0_321:
	v_cmp_ge_i32_e64 s[40:41], s59, v211
	s_and_b64 s[6:7], s[2:3], s[40:41]
	s_andn2_b64 s[10:11], s[44:45], exec
	s_and_b64 s[40:41], s[2:3], exec
	s_or_b64 s[44:45], s[10:11], s[40:41]
	s_and_saveexec_b64 s[46:47], s[6:7]
	s_cbranch_execz .LBB0_320
	v_cmp_lt_i32_e64 s[50:51], v211, v186
	v_cmp_ge_i32_e64 s[40:41], v211, v186
	s_and_saveexec_b64 s[52:53], s[40:41]
	s_cbranch_execz .LBB0_328
	ds_read_b32 v0, v210 offset:252
	s_mov_b64 s[2:3], -1
	s_waitcnt lgkmcnt(0)
	v_sub_f32_e32 v144, v16, v0
	v_pk_add_f32 v[2:3], v[160:161], v[144:145]
	s_nop 0
	v_cmp_lt_f32_e64 s[40:41], v2, v3
	s_cmp_lg_u64 s[40:41], exec
	s_cbranch_scc0 .LBB0_327
	v_add_u32_e32 v214, s64, v212
	v_add_u32_e32 v0, v210, v148
	ds_read_b128 v[2:5], v214
	ds_read_b128 v[228:231], v214 offset:4608
	ds_read_b128 v[6:9], v214 offset:32
	ds_read_b128 v[232:235], v214 offset:4640
	ds_read_b128 v[10:13], v214 offset:64
	ds_read_b128 v[236:239], v214 offset:4672
	ds_read_b128 v[224:227], v214 offset:96
	ds_read_b128 v[240:243], v214 offset:4704
	v_add_u32_e32 v252, s64, v213
	v_add_u32_e32 v253, 0x3000, v252
	s_waitcnt lgkmcnt(6)
	v_mfma_f32_32x32x16_bf16 v[64:79], v[2:5], v[128:131], 0
	ds_read_b128 v[2:5], v0
	v_mfma_f32_32x32x16_bf16 v[80:95], v[228:231], v[128:131], 0
	ds_read_b128 v[228:231], v0 offset:128
	s_waitcnt lgkmcnt(6)
	v_mfma_f32_32x32x16_bf16 v[64:79], v[6:9], v[132:135], v[64:79]
	ds_read_b128 v[6:9], v0 offset:32
	v_mfma_f32_32x32x16_bf16 v[80:95], v[232:235], v[132:135], v[80:95]
	ds_read_b128 v[232:235], v0 offset:160
	s_waitcnt lgkmcnt(6)
	v_mfma_f32_32x32x16_bf16 v[64:79], v[10:13], v[136:139], v[64:79]
	ds_read_b128 v[10:13], v0 offset:64
	v_mfma_f32_32x32x16_bf16 v[80:95], v[236:239], v[136:139], v[80:95]
	ds_read_b128 v[236:239], v0 offset:192
	s_waitcnt lgkmcnt(6)
	v_mfma_f32_32x32x16_bf16 v[64:79], v[224:227], v[140:143], v[64:79]
	ds_read_b128 v[224:227], v0 offset:96
	v_mfma_f32_32x32x16_bf16 v[80:95], v[240:243], v[140:143], v[80:95]
	ds_read_b128 v[240:243], v0 offset:224
	s_waitcnt lgkmcnt(0)
	v_pk_add_f32 v[2:3], v[16:17], v[2:3] neg_lo:[0,1] neg_hi:[0,1]
	v_pk_add_f32 v[4:5], v[50:51], v[4:5] neg_lo:[0,1] neg_hi:[0,1]
	v_pk_add_f32 v[6:7], v[52:53], v[6:7] neg_lo:[0,1] neg_hi:[0,1]
	v_pk_add_f32 v[8:9], v[54:55], v[8:9] neg_lo:[0,1] neg_hi:[0,1]
	v_pk_add_f32 v[10:11], v[56:57], v[10:11] neg_lo:[0,1] neg_hi:[0,1]
	v_pk_add_f32 v[12:13], v[58:59], v[12:13] neg_lo:[0,1] neg_hi:[0,1]
	v_pk_add_f32 v[224:225], v[60:61], v[224:225] neg_lo:[0,1] neg_hi:[0,1]
	v_pk_add_f32 v[226:227], v[62:63], v[226:227] neg_lo:[0,1] neg_hi:[0,1]
	v_pk_add_f32 v[228:229], v[16:17], v[228:229] neg_lo:[0,1] neg_hi:[0,1]
	v_pk_add_f32 v[230:231], v[50:51], v[230:231] neg_lo:[0,1] neg_hi:[0,1]
	v_pk_add_f32 v[232:233], v[52:53], v[232:233] neg_lo:[0,1] neg_hi:[0,1]
	v_pk_add_f32 v[234:235], v[54:55], v[234:235] neg_lo:[0,1] neg_hi:[0,1]
	v_pk_add_f32 v[236:237], v[56:57], v[236:237] neg_lo:[0,1] neg_hi:[0,1]
	v_pk_add_f32 v[238:239], v[58:59], v[238:239] neg_lo:[0,1] neg_hi:[0,1]
	v_pk_add_f32 v[240:241], v[60:61], v[240:241] neg_lo:[0,1] neg_hi:[0,1]
	v_pk_add_f32 v[242:243], v[62:63], v[242:243] neg_lo:[0,1] neg_hi:[0,1]
	v_pk_add_f32 v[64:65], v[64:65], v[2:3]
	v_pk_add_f32 v[66:67], v[66:67], v[4:5]
	v_pk_add_f32 v[68:69], v[68:69], v[6:7]
	v_pk_add_f32 v[70:71], v[70:71], v[8:9]
	v_pk_add_f32 v[72:73], v[72:73], v[10:11]
	v_pk_add_f32 v[74:75], v[74:75], v[12:13]
	v_pk_add_f32 v[76:77], v[76:77], v[224:225]
	v_pk_add_f32 v[78:79], v[78:79], v[226:227]
	v_pk_add_f32 v[80:81], v[80:81], v[228:229]
	v_pk_add_f32 v[82:83], v[82:83], v[230:231]
	v_pk_add_f32 v[84:85], v[84:85], v[232:233]
	v_pk_add_f32 v[86:87], v[86:87], v[234:235]
	v_pk_add_f32 v[88:89], v[88:89], v[236:237]
	v_pk_add_f32 v[90:91], v[90:91], v[238:239]
	v_pk_add_f32 v[92:93], v[92:93], v[240:241]
	v_pk_add_f32 v[94:95], v[94:95], v[242:243]
	v_add3_u32 v0, v205, s63, -1
	v_cmp_lt_i32_e64 s[40:41], s58, v0
	s_and_saveexec_b64 s[2:3], s[40:41]
	s_cbranch_execz .LBB0_326
	v_add_u32_e32 v0, s63, v206
	v_subrev_u32_e32 v15, 32, v0
	v_subrev_u32_e32 v14, 64, v0
	v_cmp_le_i32_e64 s[40:41], v15, v189
	s_nop 1
	v_cndmask_b32_e64 v80, v177, v80, s[40:41]
	v_cmp_lt_i32_e64 s[40:41], v14, v189
	s_nop 1
	v_cndmask_b32_e64 v65, v177, v65, s[40:41]
	v_cmp_le_i32_e64 s[40:41], v14, v189
	v_subrev_u32_e32 v14, 31, v0
	s_nop 0
	v_cndmask_b32_e64 v64, v177, v64, s[40:41]
	v_cmp_le_i32_e64 s[40:41], v14, v189
	v_subrev_u32_e32 v14, 62, v0
	s_nop 0
	v_cndmask_b32_e64 v81, v177, v81, s[40:41]
	v_cmp_le_i32_e64 s[40:41], v14, v189
	v_subrev_u32_e32 v14, 30, v0
	s_nop 0
	v_cndmask_b32_e64 v66, v177, v66, s[40:41]
	v_cmp_le_i32_e64 s[40:41], v14, v189
	v_subrev_u32_e32 v14, 61, v0
	s_nop 0
	v_cndmask_b32_e64 v82, v177, v82, s[40:41]
	v_cmp_le_i32_e64 s[40:41], v14, v189
	v_subrev_u32_e32 v14, 29, v0
	s_nop 0
	v_cndmask_b32_e64 v67, v177, v67, s[40:41]
	v_cmp_le_i32_e64 s[40:41], v14, v189
	v_subrev_u32_e32 v14, 56, v0
	s_nop 0
	v_cndmask_b32_e64 v83, v177, v83, s[40:41]
	v_cmp_le_i32_e64 s[40:41], v14, v189
	v_subrev_u32_e32 v14, 24, v0
	s_nop 0
	v_cndmask_b32_e64 v68, v177, v68, s[40:41]
	v_cmp_le_i32_e64 s[40:41], v14, v189
	v_subrev_u32_e32 v14, 55, v0
	s_nop 0
	v_cndmask_b32_e64 v84, v177, v84, s[40:41]
	v_cmp_le_i32_e64 s[40:41], v14, v189
	v_subrev_u32_e32 v14, 23, v0
	s_nop 0
	v_cndmask_b32_e64 v69, v177, v69, s[40:41]
	v_cmp_le_i32_e64 s[40:41], v14, v189
	v_subrev_u32_e32 v14, 54, v0
	s_nop 0
	v_cndmask_b32_e64 v85, v177, v85, s[40:41]
	v_cmp_le_i32_e64 s[40:41], v14, v189
	v_subrev_u32_e32 v14, 22, v0
	s_nop 0
	v_cndmask_b32_e64 v70, v177, v70, s[40:41]
	v_cmp_le_i32_e64 s[40:41], v14, v189
	v_subrev_u32_e32 v14, 53, v0
	s_nop 0
	v_cndmask_b32_e64 v86, v177, v86, s[40:41]
	v_cmp_le_i32_e64 s[40:41], v14, v189
	v_subrev_u32_e32 v14, 21, v0
	s_nop 0
	v_cndmask_b32_e64 v71, v177, v71, s[40:41]
	v_cmp_le_i32_e64 s[40:41], v14, v189
	v_subrev_u32_e32 v14, 48, v0
	s_nop 0
	v_cndmask_b32_e64 v87, v177, v87, s[40:41]
	v_cmp_le_i32_e64 s[40:41], v14, v189
	v_add_u32_e32 v14, -16, v0
	s_nop 0
	v_cndmask_b32_e64 v72, v177, v72, s[40:41]
	v_cmp_le_i32_e64 s[40:41], v14, v189
	v_subrev_u32_e32 v14, 47, v0
	s_nop 0
	v_cndmask_b32_e64 v88, v177, v88, s[40:41]
	v_cmp_le_i32_e64 s[40:41], v14, v189
	v_add_u32_e32 v14, -15, v0
	s_nop 0
	v_cndmask_b32_e64 v73, v177, v73, s[40:41]
	v_cmp_le_i32_e64 s[40:41], v14, v189
	v_subrev_u32_e32 v14, 46, v0
	s_nop 0
	v_cndmask_b32_e64 v89, v177, v89, s[40:41]
	v_cmp_le_i32_e64 s[40:41], v14, v189
	v_add_u32_e32 v14, -14, v0
	s_nop 0
	v_cndmask_b32_e64 v74, v177, v74, s[40:41]
	v_cmp_le_i32_e64 s[40:41], v14, v189
	v_subrev_u32_e32 v14, 45, v0
	s_nop 0
	v_cndmask_b32_e64 v90, v177, v90, s[40:41]
	v_cmp_le_i32_e64 s[40:41], v14, v189
	v_add_u32_e32 v14, -13, v0
	s_nop 0
	v_cndmask_b32_e64 v75, v177, v75, s[40:41]
	v_cmp_le_i32_e64 s[40:41], v14, v189
	v_subrev_u32_e32 v14, 40, v0
	s_nop 0
	v_cndmask_b32_e64 v91, v177, v91, s[40:41]
	v_cmp_le_i32_e64 s[40:41], v14, v189
	v_add_u32_e32 v14, -8, v0
	s_nop 0
	v_cndmask_b32_e64 v76, v177, v76, s[40:41]
	v_cmp_le_i32_e64 s[40:41], v14, v189
	v_subrev_u32_e32 v14, 39, v0
	s_nop 0
	v_cndmask_b32_e64 v92, v177, v92, s[40:41]
	v_cmp_le_i32_e64 s[40:41], v14, v189
	v_add_u32_e32 v14, -7, v0
	s_nop 0
	v_cndmask_b32_e64 v77, v177, v77, s[40:41]
	v_cmp_le_i32_e64 s[40:41], v14, v189
	v_subrev_u32_e32 v14, 38, v0
	s_nop 0
	v_cndmask_b32_e64 v93, v177, v93, s[40:41]
	v_cmp_le_i32_e64 s[40:41], v14, v189
	v_add_u32_e32 v14, -6, v0
	s_nop 0
	v_cndmask_b32_e64 v78, v177, v78, s[40:41]
	v_cmp_le_i32_e64 s[40:41], v14, v189
	v_subrev_u32_e32 v14, 37, v0
	v_add_u32_e32 v0, -5, v0
	v_cndmask_b32_e64 v94, v177, v94, s[40:41]
	v_cmp_le_i32_e64 s[40:41], v14, v189
	s_nop 1
	v_cndmask_b32_e64 v79, v177, v79, s[40:41]
	v_cmp_le_i32_e64 s[40:41], v0, v189
	s_nop 1
	v_cndmask_b32_e64 v95, v177, v95, s[40:41]
.LBB0_326:
	s_or_b64 exec, exec, s[2:3]
	s_mov_b64 s[2:3], 0
	v_max3_f32 v0, v64, v65, v66
	v_max3_f32 v14, v80, v81, v82
	v_max3_f32 v0, v0, v67, v68
	v_max3_f32 v14, v14, v83, v84
	v_max3_f32 v0, v0, v69, v70
	v_max3_f32 v14, v14, v85, v86
	v_max3_f32 v0, v0, v71, v72
	v_max3_f32 v14, v14, v87, v88
	v_max3_f32 v0, v0, v73, v74
	v_max3_f32 v14, v14, v89, v90
	v_max3_f32 v0, v0, v75, v76
	v_max3_f32 v14, v14, v91, v92
	v_max3_f32 v0, v0, v77, v78
	v_max3_f32 v14, v14, v93, v94
	v_max3_f32 v0, v0, v79, v95
	v_max_f32_e32 v0, v0, v14
	ds_bpermute_b32 v14, v187, v0
	ds_read2_b64 v[2:5], v252 offset1:2
	ds_read2_b64 v[6:9], v253 offset0:64 offset1:66
	ds_read2_b64 v[10:13], v252 offset0:8 offset1:10
	ds_read2_b64 v[224:227], v253 offset0:72 offset1:74
	ds_read2_b64 v[228:231], v252 offset0:4 offset1:6
	ds_read2_b64 v[232:235], v253 offset0:68 offset1:70
	ds_read2_b64 v[236:239], v252 offset0:12 offset1:14
	ds_read2_b64 v[240:243], v253 offset0:76 offset1:78
	s_waitcnt lgkmcnt(8)
	v_max3_f32 v144, v161, v0, v14
	v_sub_f32_e32 v0, v161, v144
	v_mov_b32_e32 v161, v144
	v_exp_f32_e32 v0, v0
	v_pk_add_f32 v[64:65], v[64:65], v[144:145] op_sel_hi:[1,0] neg_lo:[0,1] neg_hi:[0,1]
	v_pk_add_f32 v[66:67], v[66:67], v[144:145] op_sel_hi:[1,0] neg_lo:[0,1] neg_hi:[0,1]
	v_pk_add_f32 v[68:69], v[68:69], v[144:145] op_sel_hi:[1,0] neg_lo:[0,1] neg_hi:[0,1]
	v_pk_add_f32 v[70:71], v[70:71], v[144:145] op_sel_hi:[1,0] neg_lo:[0,1] neg_hi:[0,1]
	v_pk_add_f32 v[72:73], v[72:73], v[144:145] op_sel_hi:[1,0] neg_lo:[0,1] neg_hi:[0,1]
	v_pk_add_f32 v[74:75], v[74:75], v[144:145] op_sel_hi:[1,0] neg_lo:[0,1] neg_hi:[0,1]
	v_pk_add_f32 v[76:77], v[76:77], v[144:145] op_sel_hi:[1,0] neg_lo:[0,1] neg_hi:[0,1]
	v_pk_add_f32 v[78:79], v[78:79], v[144:145] op_sel_hi:[1,0] neg_lo:[0,1] neg_hi:[0,1]
	v_pk_add_f32 v[80:81], v[80:81], v[144:145] op_sel_hi:[1,0] neg_lo:[0,1] neg_hi:[0,1]
	v_pk_add_f32 v[82:83], v[82:83], v[144:145] op_sel_hi:[1,0] neg_lo:[0,1] neg_hi:[0,1]
	v_pk_add_f32 v[84:85], v[84:85], v[144:145] op_sel_hi:[1,0] neg_lo:[0,1] neg_hi:[0,1]
	v_pk_add_f32 v[86:87], v[86:87], v[144:145] op_sel_hi:[1,0] neg_lo:[0,1] neg_hi:[0,1]
	v_pk_add_f32 v[88:89], v[88:89], v[144:145] op_sel_hi:[1,0] neg_lo:[0,1] neg_hi:[0,1]
	v_pk_add_f32 v[90:91], v[90:91], v[144:145] op_sel_hi:[1,0] neg_lo:[0,1] neg_hi:[0,1]
	v_pk_add_f32 v[92:93], v[92:93], v[144:145] op_sel_hi:[1,0] neg_lo:[0,1] neg_hi:[0,1]
	v_pk_add_f32 v[94:95], v[94:95], v[144:145] op_sel_hi:[1,0] neg_lo:[0,1] neg_hi:[0,1]
	v_exp_f32_e32 v64, v64
	v_exp_f32_e32 v65, v65
	v_exp_f32_e32 v66, v66
	v_exp_f32_e32 v67, v67
	v_exp_f32_e32 v68, v68
	v_exp_f32_e32 v69, v69
	v_exp_f32_e32 v70, v70
	v_exp_f32_e32 v71, v71
	v_exp_f32_e32 v80, v80
	v_exp_f32_e32 v81, v81
	v_exp_f32_e32 v82, v82
	v_exp_f32_e32 v83, v83
	v_exp_f32_e32 v84, v84
	v_exp_f32_e32 v85, v85
	v_exp_f32_e32 v86, v86
	v_exp_f32_e32 v87, v87
	v_pk_mul_f32 v[34:35], v[34:35], v[0:1] op_sel_hi:[1,0]
	v_pk_mul_f32 v[36:37], v[36:37], v[0:1] op_sel_hi:[1,0]
	v_pk_mul_f32 v[38:39], v[38:39], v[0:1] op_sel_hi:[1,0]
	v_pk_mul_f32 v[40:41], v[40:41], v[0:1] op_sel_hi:[1,0]
	v_pk_mul_f32 v[42:43], v[42:43], v[0:1] op_sel_hi:[1,0]
	v_pk_mul_f32 v[44:45], v[44:45], v[0:1] op_sel_hi:[1,0]
	v_pk_mul_f32 v[46:47], v[46:47], v[0:1] op_sel_hi:[1,0]
	v_pk_mul_f32 v[48:49], v[48:49], v[0:1] op_sel_hi:[1,0]
	v_exp_f32_e32 v72, v72
	v_exp_f32_e32 v73, v73
	v_exp_f32_e32 v74, v74
	v_exp_f32_e32 v75, v75
	v_exp_f32_e32 v76, v76
	v_exp_f32_e32 v77, v77
	v_exp_f32_e32 v78, v78
	v_exp_f32_e32 v79, v79
	v_pk_mul_f32 v[18:19], v[18:19], v[0:1] op_sel_hi:[1,0]
	v_pk_mul_f32 v[20:21], v[20:21], v[0:1] op_sel_hi:[1,0]
	v_pk_mul_f32 v[22:23], v[22:23], v[0:1] op_sel_hi:[1,0]
	v_pk_mul_f32 v[24:25], v[24:25], v[0:1] op_sel_hi:[1,0]
	v_pk_mul_f32 v[26:27], v[26:27], v[0:1] op_sel_hi:[1,0]
	v_pk_mul_f32 v[28:29], v[28:29], v[0:1] op_sel_hi:[1,0]
	v_pk_mul_f32 v[30:31], v[30:31], v[0:1] op_sel_hi:[1,0]
	v_pk_mul_f32 v[32:33], v[32:33], v[0:1] op_sel_hi:[1,0]
	v_exp_f32_e32 v88, v88
	v_exp_f32_e32 v89, v89
	v_exp_f32_e32 v90, v90
	v_exp_f32_e32 v91, v91
	v_exp_f32_e32 v92, v92
	v_exp_f32_e32 v93, v93
	v_exp_f32_e32 v94, v94
	v_exp_f32_e32 v95, v95
	v_pk_add_f32 v[214:215], v[64:65], v[80:81]
	v_pk_add_f32 v[216:217], v[66:67], v[82:83]
	v_pk_add_f32 v[244:245], v[68:69], v[84:85]
	v_pk_add_f32 v[246:247], v[70:71], v[86:87]
	v_cvt_pk_bf16_f32 v64, v64, v65
	v_cvt_pk_bf16_f32 v65, v66, v67
	v_cvt_pk_bf16_f32 v66, v68, v69
	v_cvt_pk_bf16_f32 v67, v70, v71
	v_cvt_pk_bf16_f32 v80, v80, v81
	v_cvt_pk_bf16_f32 v81, v82, v83
	v_cvt_pk_bf16_f32 v82, v84, v85
	v_cvt_pk_bf16_f32 v83, v86, v87
	v_pk_add_f32 v[248:249], v[72:73], v[88:89]
	v_pk_add_f32 v[250:251], v[74:75], v[90:91]
	v_pk_add_f32 v[14:15], v[76:77], v[92:93]
	v_pk_add_f32 v[218:219], v[78:79], v[94:95]
	s_waitcnt lgkmcnt(4)
	v_mfma_f32_32x32x16_bf16 v[34:49], v[2:5], v[64:67], v[34:49]
	v_mfma_f32_32x32x16_bf16 v[18:33], v[6:9], v[64:67], v[18:33]
	v_mfma_f32_32x32x16_bf16 v[34:49], v[10:13], v[80:83], v[34:49]
	v_mfma_f32_32x32x16_bf16 v[18:33], v[224:227], v[80:83], v[18:33]
	v_cvt_pk_bf16_f32 v68, v72, v73
	v_cvt_pk_bf16_f32 v69, v74, v75
	v_cvt_pk_bf16_f32 v70, v76, v77
	v_cvt_pk_bf16_f32 v71, v78, v79
	v_cvt_pk_bf16_f32 v84, v88, v89
	v_cvt_pk_bf16_f32 v85, v90, v91
	v_cvt_pk_bf16_f32 v86, v92, v93
	v_cvt_pk_bf16_f32 v87, v94, v95
	v_add_f32_e32 v144, 0, v214
	v_add_f32_e32 v144, v215, v144
	v_add_f32_e32 v144, v216, v144
	v_add_f32_e32 v144, v217, v144
	v_add_f32_e32 v144, v244, v144
	v_add_f32_e32 v144, v245, v144
	v_add_f32_e32 v144, v246, v144
	v_add_f32_e32 v144, v247, v144
	s_waitcnt lgkmcnt(0)
	v_mfma_f32_32x32x16_bf16 v[34:49], v[228:231], v[68:71], v[34:49]
	v_mfma_f32_32x32x16_bf16 v[18:33], v[232:235], v[68:71], v[18:33]
	v_mfma_f32_32x32x16_bf16 v[34:49], v[236:239], v[84:87], v[34:49]
	v_mfma_f32_32x32x16_bf16 v[18:33], v[240:243], v[84:87], v[18:33]
	v_add_f32_e32 v144, v248, v144
	v_add_f32_e32 v144, v249, v144
	v_add_f32_e32 v144, v250, v144
	v_add_f32_e32 v144, v251, v144
	v_add_f32_e32 v144, v14, v144
	v_add_f32_e32 v144, v15, v144
	v_add_f32_e32 v144, v218, v144
	v_add_f32_e32 v144, v219, v144
	v_fma_f32 v202, v202, v0, v144
